# attention sample items: K score loop keeps four groups of 16-byte loads in flight (three into registers only the prompt path uses) instead of one fully-drained group at a time
# speedup vs baseline: 1.0006x; 1.0006x over previous
; DI void attn_sample_item(const Params& p, int l, int item, char* smem, bfr* Obuf) {
;     ...
; #pragma unroll 8
;   for (int ps = 0; ps < 16; ++ps) {
;     int mem = wid * 64 + ps * 4 + grp;
;     const float4* kr = (const float4*)(Kb + (size_t)mem * 1024);
;     float d = 0.f;
; #pragma unroll
;     for (int j = 0; j < 4; ++j) {
;       float4 k4 = kr[j * 16 + l16];
;       d += k4.x * q4[j].x + k4.y * q4[j].y + k4.z * q4[j].z + k4.w * q4[j].w;
;     }
;     d += __shfl_xor(d, 8);
;     d += __shfl_xor(d, 4);
;     d += __shfl_xor(d, 2);
;     d += __shfl_xor(d, 1);
;     if (l16 == 0) sc[mem] = d * 0.0625f;
;   }
.LBB0_1001:
	v_lshl_add_u64 v[54:55], v[18:19], 0, s[22:23]
	s_waitcnt lgkmcnt(0)
	global_load_dwordx4 v[42:45], v[54:55], off
	global_load_dwordx4 v[46:49], v[54:55], off offset:256
	global_load_dwordx4 v[50:53], v[54:55], off offset:512
	s_nop 0
	global_load_dwordx4 v[54:57], v[54:55], off offset:768
	v_lshl_add_u64 v[208:209], v[20:21], 0, s[22:23]
	global_load_dwordx4 v[108:111], v[208:209], off
	global_load_dwordx4 v[142:145], v[208:209], off offset:256
	global_load_dwordx4 v[156:159], v[208:209], off offset:512
	global_load_dwordx4 v[200:203], v[208:209], off offset:768
	v_lshl_add_u64 v[208:209], v[24:25], 0, s[22:23]
	global_load_dwordx4 v[204:207], v[208:209], off
	global_load_dwordx4 v[216:219], v[208:209], off offset:256
	global_load_dwordx4 v[220:223], v[208:209], off offset:512
	global_load_dwordx4 v[224:227], v[208:209], off offset:768
	v_lshl_add_u64 v[208:209], v[28:29], 0, s[22:23]
	global_load_dwordx4 v[228:231], v[208:209], off
	global_load_dwordx4 v[232:235], v[208:209], off offset:256
	global_load_dwordx4 v[236:239], v[208:209], off offset:512
	global_load_dwordx4 v[240:243], v[208:209], off offset:768
	s_waitcnt vmcnt(15) lgkmcnt(3)
	v_mul_f32_e32 v41, v1, v43
	s_waitcnt vmcnt(14) lgkmcnt(2)
	v_mul_f32_e32 v43, v5, v47
	v_fmac_f32_e32 v41, v0, v42
	s_waitcnt vmcnt(13) lgkmcnt(1)
	v_mul_f32_e32 v47, v9, v51
	v_fmac_f32_e32 v43, v4, v46
	v_fmac_f32_e32 v41, v2, v44
	s_waitcnt vmcnt(12) lgkmcnt(0)
	v_mul_f32_e32 v51, v13, v55
	v_fmac_f32_e32 v47, v8, v50
	v_fmac_f32_e32 v43, v6, v48
	v_fmac_f32_e32 v41, v3, v45
	v_fmac_f32_e32 v51, v12, v54
	v_fmac_f32_e32 v47, v10, v52
	v_fmac_f32_e32 v43, v7, v49
	v_add_f32_e32 v41, 0, v41
	v_fmac_f32_e32 v51, v14, v56
	v_fmac_f32_e32 v47, v11, v53
	v_add_f32_e32 v41, v41, v43
	v_add_f32_e32 v41, v41, v47
	v_fmac_f32_e32 v51, v15, v57
	v_add_f32_e32 v41, v41, v51
	ds_bpermute_b32 v42, v34, v41
	s_waitcnt lgkmcnt(0)
	v_add_f32_e32 v41, v41, v42
	ds_bpermute_b32 v42, v35, v41
	s_waitcnt lgkmcnt(0)
	v_add_f32_e32 v41, v41, v42
	ds_bpermute_b32 v42, v36, v41
	s_waitcnt lgkmcnt(0)
	v_add_f32_e32 v41, v41, v42
	ds_bpermute_b32 v42, v37, v41
	s_and_saveexec_b64 s[24:25], s[0:1]
	s_cbranch_execz .LBB0_1003
	s_waitcnt lgkmcnt(0)
	v_add_f32_e32 v41, v41, v42
	v_mul_f32_e32 v41, 0x3d800000, v41
	ds_write_b32 v40, v41
.LBB0_1003:
	s_or_b64 exec, exec, s[24:25]
	s_waitcnt vmcnt(11)
	v_mul_f32_e32 v41, v1, v109
	s_waitcnt vmcnt(10)
	v_mul_f32_e32 v43, v5, v143
	v_fmac_f32_e32 v41, v0, v108
	s_waitcnt vmcnt(9)
	v_mul_f32_e32 v47, v9, v157
	v_fmac_f32_e32 v43, v4, v142
	v_fmac_f32_e32 v41, v2, v110
	s_waitcnt vmcnt(8)
	v_mul_f32_e32 v51, v13, v201
	v_fmac_f32_e32 v47, v8, v156
	v_fmac_f32_e32 v43, v6, v144
	v_fmac_f32_e32 v41, v3, v111
	v_fmac_f32_e32 v51, v12, v200
	v_fmac_f32_e32 v47, v10, v158
	v_fmac_f32_e32 v43, v7, v145
	v_add_f32_e32 v41, 0, v41
	v_fmac_f32_e32 v51, v14, v202
	v_fmac_f32_e32 v47, v11, v159
	v_add_f32_e32 v41, v41, v43
	v_add_f32_e32 v41, v41, v47
	v_fmac_f32_e32 v51, v15, v203
	v_add_f32_e32 v41, v41, v51
	ds_bpermute_b32 v42, v34, v41
	s_waitcnt lgkmcnt(0)
	v_add_f32_e32 v41, v41, v42
	ds_bpermute_b32 v42, v35, v41
	s_waitcnt lgkmcnt(0)
	v_add_f32_e32 v41, v41, v42
	ds_bpermute_b32 v42, v36, v41
	s_waitcnt lgkmcnt(0)
	v_add_f32_e32 v41, v41, v42
	ds_bpermute_b32 v42, v37, v41
	s_and_saveexec_b64 s[24:25], s[0:1]
	s_cbranch_execz .LBB0_1005
	s_waitcnt lgkmcnt(0)
	v_add_f32_e32 v41, v41, v42
	v_mul_f32_e32 v41, 0x3d800000, v41
	ds_write_b32 v40, v41 offset:16
.LBB0_1005:
	s_or_b64 exec, exec, s[24:25]
	s_waitcnt vmcnt(7)
	v_mul_f32_e32 v41, v1, v205
	s_waitcnt vmcnt(6)
	v_mul_f32_e32 v43, v5, v217
	v_fmac_f32_e32 v41, v0, v204
	s_waitcnt vmcnt(5)
	v_mul_f32_e32 v47, v9, v221
	v_fmac_f32_e32 v43, v4, v216
	v_fmac_f32_e32 v41, v2, v206
	s_waitcnt vmcnt(4)
	v_mul_f32_e32 v51, v13, v225
	v_fmac_f32_e32 v47, v8, v220
	v_fmac_f32_e32 v43, v6, v218
	v_fmac_f32_e32 v41, v3, v207
	v_fmac_f32_e32 v51, v12, v224
	v_fmac_f32_e32 v47, v10, v222
	v_fmac_f32_e32 v43, v7, v219
	v_add_f32_e32 v41, 0, v41
	v_fmac_f32_e32 v51, v14, v226
	v_fmac_f32_e32 v47, v11, v223
	v_add_f32_e32 v41, v41, v43
	v_add_f32_e32 v41, v41, v47
	v_fmac_f32_e32 v51, v15, v227
	v_add_f32_e32 v41, v41, v51
	ds_bpermute_b32 v42, v34, v41
	s_waitcnt lgkmcnt(0)
	v_add_f32_e32 v41, v41, v42
	ds_bpermute_b32 v42, v35, v41
	s_waitcnt lgkmcnt(0)
	v_add_f32_e32 v41, v41, v42
	ds_bpermute_b32 v42, v36, v41
	s_waitcnt lgkmcnt(0)
	v_add_f32_e32 v41, v41, v42
	ds_bpermute_b32 v42, v37, v41
	s_and_saveexec_b64 s[24:25], s[0:1]
	s_cbranch_execz .LBB0_1007
	s_waitcnt lgkmcnt(0)
	v_add_f32_e32 v41, v41, v42
	v_mul_f32_e32 v41, 0x3d800000, v41
	ds_write_b32 v40, v41 offset:32
.LBB0_1007:
	s_or_b64 exec, exec, s[24:25]
	s_waitcnt vmcnt(3)
	v_mul_f32_e32 v41, v1, v229
	s_waitcnt vmcnt(2)
	v_mul_f32_e32 v43, v5, v233
	v_fmac_f32_e32 v41, v0, v228
	s_waitcnt vmcnt(1)
	v_mul_f32_e32 v47, v9, v237
	v_fmac_f32_e32 v43, v4, v232
	v_fmac_f32_e32 v41, v2, v230
	s_waitcnt vmcnt(0)
	v_mul_f32_e32 v51, v13, v241
	v_fmac_f32_e32 v47, v8, v236
	v_fmac_f32_e32 v43, v6, v234
	v_fmac_f32_e32 v41, v3, v231
	v_fmac_f32_e32 v51, v12, v240
	v_fmac_f32_e32 v47, v10, v238
	v_fmac_f32_e32 v43, v7, v235
	v_add_f32_e32 v41, 0, v41
	v_fmac_f32_e32 v51, v14, v242
	v_fmac_f32_e32 v47, v11, v239
	v_add_f32_e32 v41, v41, v43
	v_add_f32_e32 v41, v41, v47
	v_fmac_f32_e32 v51, v15, v243
	v_add_f32_e32 v41, v41, v51
	ds_bpermute_b32 v42, v34, v41
	s_waitcnt lgkmcnt(0)
	v_add_f32_e32 v41, v41, v42
	ds_bpermute_b32 v42, v35, v41
	s_waitcnt lgkmcnt(0)
	v_add_f32_e32 v41, v41, v42
	ds_bpermute_b32 v42, v36, v41
	s_waitcnt lgkmcnt(0)
	v_add_f32_e32 v41, v41, v42
	ds_bpermute_b32 v42, v37, v41
	s_and_saveexec_b64 s[24:25], s[0:1]
	s_cbranch_execz .LBB0_1009
	s_waitcnt lgkmcnt(0)
	v_add_f32_e32 v41, v41, v42
	v_mul_f32_e32 v41, 0x3d800000, v41
	ds_write_b32 v40, v41 offset:48
; DI void attn_sample_item(const Params& p, int l, int item, char* smem, bfr* Obuf) {
;     ...
; #pragma unroll 8
;   for (int ps = 0; ps < 16; ++ps) {
;     int mem = wid * 64 + ps * 4 + grp;
;     const float4* kr = (const float4*)(Kb + (size_t)mem * 1024);
;     float d = 0.f;
; #pragma unroll
;     for (int j = 0; j < 4; ++j) {
;       float4 k4 = kr[j * 16 + l16];
;       d += k4.x * q4[j].x + k4.y * q4[j].y + k4.z * q4[j].z + k4.w * q4[j].w;
;     }
;     d += __shfl_xor(d, 8);
;     d += __shfl_xor(d, 4);
;     d += __shfl_xor(d, 2);
;     d += __shfl_xor(d, 1);
;     if (l16 == 0) sc[mem] = d * 0.0625f;
;   }
.LBB0_1009:
	s_or_b64 exec, exec, s[24:25]
	v_lshl_add_u64 v[54:55], v[32:33], 0, s[22:23]
	s_waitcnt lgkmcnt(0)
	global_load_dwordx4 v[42:45], v[54:55], off
	global_load_dwordx4 v[46:49], v[54:55], off offset:256
	global_load_dwordx4 v[50:53], v[54:55], off offset:512
	s_nop 0
	global_load_dwordx4 v[54:57], v[54:55], off offset:768
	v_lshl_add_u64 v[208:209], v[30:31], 0, s[22:23]
	global_load_dwordx4 v[108:111], v[208:209], off
	global_load_dwordx4 v[142:145], v[208:209], off offset:256
	global_load_dwordx4 v[156:159], v[208:209], off offset:512
	global_load_dwordx4 v[200:203], v[208:209], off offset:768
	v_lshl_add_u64 v[208:209], v[26:27], 0, s[22:23]
	global_load_dwordx4 v[204:207], v[208:209], off
	global_load_dwordx4 v[216:219], v[208:209], off offset:256
	global_load_dwordx4 v[220:223], v[208:209], off offset:512
	global_load_dwordx4 v[224:227], v[208:209], off offset:768
	v_lshl_add_u64 v[208:209], v[22:23], 0, s[22:23]
	global_load_dwordx4 v[228:231], v[208:209], off
	global_load_dwordx4 v[232:235], v[208:209], off offset:256
	global_load_dwordx4 v[236:239], v[208:209], off offset:512
	global_load_dwordx4 v[240:243], v[208:209], off offset:768
	s_waitcnt vmcnt(15)
	v_mul_f32_e32 v41, v1, v43
	s_waitcnt vmcnt(14)
	v_mul_f32_e32 v43, v5, v47
	v_fmac_f32_e32 v41, v0, v42
	s_waitcnt vmcnt(13)
	v_mul_f32_e32 v47, v9, v51
	v_fmac_f32_e32 v43, v4, v46
	v_fmac_f32_e32 v41, v2, v44
	s_waitcnt vmcnt(12)
	v_mul_f32_e32 v51, v13, v55
	v_fmac_f32_e32 v47, v8, v50
	v_fmac_f32_e32 v43, v6, v48
	v_fmac_f32_e32 v41, v3, v45
	v_fmac_f32_e32 v51, v12, v54
	v_fmac_f32_e32 v47, v10, v52
	v_fmac_f32_e32 v43, v7, v49
	v_add_f32_e32 v41, 0, v41
	v_fmac_f32_e32 v51, v14, v56
	v_fmac_f32_e32 v47, v11, v53
	v_add_f32_e32 v41, v41, v43
	v_add_f32_e32 v41, v41, v47
	v_fmac_f32_e32 v51, v15, v57
	v_add_f32_e32 v41, v41, v51
	ds_bpermute_b32 v42, v34, v41
	s_waitcnt lgkmcnt(0)
	v_add_f32_e32 v41, v41, v42
	ds_bpermute_b32 v42, v35, v41
	s_waitcnt lgkmcnt(0)
	v_add_f32_e32 v41, v41, v42
	ds_bpermute_b32 v42, v36, v41
	s_waitcnt lgkmcnt(0)
	v_add_f32_e32 v41, v41, v42
	ds_bpermute_b32 v42, v37, v41
	s_and_saveexec_b64 s[24:25], s[0:1]
	s_cbranch_execz .LBB0_1011
	s_waitcnt lgkmcnt(0)
	v_add_f32_e32 v41, v41, v42
	v_mul_f32_e32 v41, 0x3d800000, v41
	ds_write_b32 v40, v41 offset:64
.LBB0_1011:
	s_or_b64 exec, exec, s[24:25]
	s_waitcnt vmcnt(11)
	v_mul_f32_e32 v41, v1, v109
	s_waitcnt vmcnt(10)
	v_mul_f32_e32 v43, v5, v143
	v_fmac_f32_e32 v41, v0, v108
	s_waitcnt vmcnt(9)
	v_mul_f32_e32 v47, v9, v157
	v_fmac_f32_e32 v43, v4, v142
	v_fmac_f32_e32 v41, v2, v110
	s_waitcnt vmcnt(8)
	v_mul_f32_e32 v51, v13, v201
	v_fmac_f32_e32 v47, v8, v156
	v_fmac_f32_e32 v43, v6, v144
	v_fmac_f32_e32 v41, v3, v111
	v_fmac_f32_e32 v51, v12, v200
	v_fmac_f32_e32 v47, v10, v158
	v_fmac_f32_e32 v43, v7, v145
	v_add_f32_e32 v41, 0, v41
	v_fmac_f32_e32 v51, v14, v202
	v_fmac_f32_e32 v47, v11, v159
	v_add_f32_e32 v41, v41, v43
	v_add_f32_e32 v41, v41, v47
	v_fmac_f32_e32 v51, v15, v203
	v_add_f32_e32 v41, v41, v51
	ds_bpermute_b32 v42, v34, v41
	s_waitcnt lgkmcnt(0)
	v_add_f32_e32 v41, v41, v42
	ds_bpermute_b32 v42, v35, v41
	s_waitcnt lgkmcnt(0)
	v_add_f32_e32 v41, v41, v42
	ds_bpermute_b32 v42, v36, v41
	s_waitcnt lgkmcnt(0)
	v_add_f32_e32 v41, v41, v42
	ds_bpermute_b32 v42, v37, v41
	s_and_saveexec_b64 s[24:25], s[0:1]
	s_cbranch_execz .LBB0_1013
	s_waitcnt lgkmcnt(0)
	v_add_f32_e32 v41, v41, v42
	v_mul_f32_e32 v41, 0x3d800000, v41
	ds_write_b32 v40, v41 offset:80
.LBB0_1013:
	s_or_b64 exec, exec, s[24:25]
	s_waitcnt vmcnt(7)
	v_mul_f32_e32 v41, v1, v205
	s_waitcnt vmcnt(6)
	v_mul_f32_e32 v43, v5, v217
	v_fmac_f32_e32 v41, v0, v204
	s_waitcnt vmcnt(5)
	v_mul_f32_e32 v47, v9, v221
	v_fmac_f32_e32 v43, v4, v216
	v_fmac_f32_e32 v41, v2, v206
	s_waitcnt vmcnt(4)
	v_mul_f32_e32 v51, v13, v225
	v_fmac_f32_e32 v47, v8, v220
	v_fmac_f32_e32 v43, v6, v218
	v_fmac_f32_e32 v41, v3, v207
	v_fmac_f32_e32 v51, v12, v224
	v_fmac_f32_e32 v47, v10, v222
	v_fmac_f32_e32 v43, v7, v219
	v_add_f32_e32 v41, 0, v41
	v_fmac_f32_e32 v51, v14, v226
	v_fmac_f32_e32 v47, v11, v223
	v_add_f32_e32 v41, v41, v43
	v_add_f32_e32 v41, v41, v47
	v_fmac_f32_e32 v51, v15, v227
	v_add_f32_e32 v41, v41, v51
	ds_bpermute_b32 v42, v34, v41
	s_waitcnt lgkmcnt(0)
	v_add_f32_e32 v41, v41, v42
	ds_bpermute_b32 v42, v35, v41
	s_waitcnt lgkmcnt(0)
	v_add_f32_e32 v41, v41, v42
	ds_bpermute_b32 v42, v36, v41
	s_waitcnt lgkmcnt(0)
	v_add_f32_e32 v41, v41, v42
	ds_bpermute_b32 v42, v37, v41
	s_and_saveexec_b64 s[24:25], s[0:1]
	s_cbranch_execz .LBB0_1015
	s_waitcnt lgkmcnt(0)
	v_add_f32_e32 v41, v41, v42
	v_mul_f32_e32 v41, 0x3d800000, v41
	ds_write_b32 v40, v41 offset:96
.LBB0_1015:
	s_or_b64 exec, exec, s[24:25]
	s_waitcnt vmcnt(3)
	v_mul_f32_e32 v41, v1, v229
	s_waitcnt vmcnt(2)
	v_mul_f32_e32 v43, v5, v233
	v_fmac_f32_e32 v41, v0, v228
	s_waitcnt vmcnt(1)
	v_mul_f32_e32 v47, v9, v237
	v_fmac_f32_e32 v43, v4, v232
	v_fmac_f32_e32 v41, v2, v230
	s_waitcnt vmcnt(0)
	v_mul_f32_e32 v51, v13, v241
	v_fmac_f32_e32 v47, v8, v236
	v_fmac_f32_e32 v43, v6, v234
	v_fmac_f32_e32 v41, v3, v231
	v_fmac_f32_e32 v51, v12, v240
	v_fmac_f32_e32 v47, v10, v238
	v_fmac_f32_e32 v43, v7, v235
	v_add_f32_e32 v41, 0, v41
	v_fmac_f32_e32 v51, v14, v242
	v_fmac_f32_e32 v47, v11, v239
	v_add_f32_e32 v41, v41, v43
	v_add_f32_e32 v41, v41, v47
	v_fmac_f32_e32 v51, v15, v243
	v_add_f32_e32 v41, v41, v51
	ds_bpermute_b32 v42, v34, v41
	s_waitcnt lgkmcnt(0)
	v_add_f32_e32 v41, v41, v42
	ds_bpermute_b32 v42, v35, v41
	s_waitcnt lgkmcnt(0)
	v_add_f32_e32 v41, v41, v42
	ds_bpermute_b32 v42, v36, v41
	s_waitcnt lgkmcnt(0)
	v_add_f32_e32 v41, v41, v42
	ds_bpermute_b32 v42, v37, v41
	s_and_saveexec_b64 s[24:25], s[0:1]
	s_cbranch_execz .LBB0_1000
	s_waitcnt lgkmcnt(0)
	v_add_f32_e32 v41, v41, v42
	v_mul_f32_e32 v41, 0x3d800000, v41
	ds_write_b32 v40, v41 offset:112
	s_branch .LBB0_1000

; DI void attn_sample_item(const Params& p, int l, int item, char* smem, bfr* Obuf) {
;     ...
; #pragma unroll 8
;   for (int ps = 0; ps < 16; ++ps) {
;     int mem = wid * 64 + ps * 4 + grp;
;     const float4* kr = (const float4*)(Kb + (size_t)mem * 1024);
;     float d = 0.f;
; #pragma unroll
;     for (int j = 0; j < 4; ++j) {
;       float4 k4 = kr[j * 16 + l16];
;       d += k4.x * q4[j].x + k4.y * q4[j].y + k4.z * q4[j].z + k4.w * q4[j].w;
;     }
;     d += __shfl_xor(d, 8);
;     d += __shfl_xor(d, 4);
;     d += __shfl_xor(d, 2);
;     d += __shfl_xor(d, 1);
;     if (l16 == 0) sc[mem] = d * 0.0625f;
;   }
.LBB0_1624:
	v_lshl_add_u64 v[58:59], v[18:19], 0, s[18:19]
	s_waitcnt lgkmcnt(0)
	global_load_dwordx4 v[42:45], v[58:59], off offset:-512
	global_load_dwordx4 v[46:49], v[58:59], off offset:-256
	global_load_dwordx4 v[50:53], v[58:59], off
	global_load_dwordx4 v[54:57], v[58:59], off offset:256
	v_lshl_add_u64 v[240:241], v[20:21], 0, s[18:19]
	global_load_dwordx4 v[108:111], v[240:241], off offset:-512
	global_load_dwordx4 v[142:145], v[240:241], off offset:-256
	global_load_dwordx4 v[156:159], v[240:241], off
	global_load_dwordx4 v[200:203], v[240:241], off offset:256
	v_lshl_add_u64 v[240:241], v[22:23], 0, s[18:19]
	global_load_dwordx4 v[204:207], v[240:241], off offset:-512
	global_load_dwordx4 v[208:211], v[240:241], off offset:-256
	global_load_dwordx4 v[212:215], v[240:241], off
	global_load_dwordx4 v[216:219], v[240:241], off offset:256
	v_lshl_add_u64 v[240:241], v[24:25], 0, s[18:19]
	global_load_dwordx4 v[224:227], v[240:241], off offset:-512
	global_load_dwordx4 v[228:231], v[240:241], off offset:-256
	global_load_dwordx4 v[232:235], v[240:241], off
	global_load_dwordx4 v[236:239], v[240:241], off offset:256
	s_waitcnt vmcnt(15) lgkmcnt(3)
	v_mul_f32_e32 v41, v1, v43
	s_waitcnt vmcnt(14) lgkmcnt(2)
	v_mul_f32_e32 v43, v5, v47
	v_fmac_f32_e32 v41, v0, v42
	s_waitcnt vmcnt(13) lgkmcnt(1)
	v_mul_f32_e32 v47, v9, v51
	v_fmac_f32_e32 v43, v4, v46
	v_fmac_f32_e32 v41, v2, v44
	s_waitcnt vmcnt(12) lgkmcnt(0)
	v_mul_f32_e32 v51, v13, v55
	v_fmac_f32_e32 v47, v8, v50
	v_fmac_f32_e32 v43, v6, v48
	v_fmac_f32_e32 v41, v3, v45
	v_fmac_f32_e32 v51, v12, v54
	v_fmac_f32_e32 v47, v10, v52
	v_fmac_f32_e32 v43, v7, v49
	v_add_f32_e32 v41, 0, v41
	v_fmac_f32_e32 v51, v14, v56
	v_fmac_f32_e32 v47, v11, v53
	v_add_f32_e32 v41, v41, v43
	v_add_f32_e32 v41, v41, v47
	v_fmac_f32_e32 v51, v15, v57
	v_add_f32_e32 v41, v41, v51
	ds_bpermute_b32 v42, v34, v41
	s_waitcnt lgkmcnt(0)
	v_add_f32_e32 v41, v41, v42
	ds_bpermute_b32 v42, v35, v41
	s_waitcnt lgkmcnt(0)
	v_add_f32_e32 v41, v41, v42
	ds_bpermute_b32 v42, v36, v41
	s_waitcnt lgkmcnt(0)
	v_add_f32_e32 v41, v41, v42
	ds_bpermute_b32 v42, v37, v41
	s_and_saveexec_b64 s[20:21], s[0:1]
	s_cbranch_execz .LBB0_1626
	s_waitcnt lgkmcnt(0)
	v_add_f32_e32 v41, v41, v42
	v_mul_f32_e32 v41, 0x3d800000, v41
	ds_write_b32 v40, v41
.LBB0_1626:
	s_or_b64 exec, exec, s[20:21]
	s_waitcnt vmcnt(11)
	v_mul_f32_e32 v41, v1, v109
	s_waitcnt vmcnt(10)
	v_mul_f32_e32 v43, v5, v143
	v_fmac_f32_e32 v41, v0, v108
	s_waitcnt vmcnt(9)
	v_mul_f32_e32 v47, v9, v157
	v_fmac_f32_e32 v43, v4, v142
	v_fmac_f32_e32 v41, v2, v110
	s_waitcnt vmcnt(8)
	v_mul_f32_e32 v51, v13, v201
	v_fmac_f32_e32 v47, v8, v156
	v_fmac_f32_e32 v43, v6, v144
	v_fmac_f32_e32 v41, v3, v111
	v_fmac_f32_e32 v51, v12, v200
	v_fmac_f32_e32 v47, v10, v158
	v_fmac_f32_e32 v43, v7, v145
	v_add_f32_e32 v41, 0, v41
	v_fmac_f32_e32 v51, v14, v202
	v_fmac_f32_e32 v47, v11, v159
	v_add_f32_e32 v41, v41, v43
	v_add_f32_e32 v41, v41, v47
	v_fmac_f32_e32 v51, v15, v203
	v_add_f32_e32 v41, v41, v51
	ds_bpermute_b32 v42, v34, v41
	s_waitcnt lgkmcnt(0)
	v_add_f32_e32 v41, v41, v42
	ds_bpermute_b32 v42, v35, v41
	s_waitcnt lgkmcnt(0)
	v_add_f32_e32 v41, v41, v42
	ds_bpermute_b32 v42, v36, v41
	s_waitcnt lgkmcnt(0)
	v_add_f32_e32 v41, v41, v42
	ds_bpermute_b32 v42, v37, v41
	s_and_saveexec_b64 s[20:21], s[0:1]
	s_cbranch_execz .LBB0_1628
	s_waitcnt lgkmcnt(0)
	v_add_f32_e32 v41, v41, v42
	v_mul_f32_e32 v41, 0x3d800000, v41
	ds_write_b32 v40, v41 offset:16
.LBB0_1628:
	s_or_b64 exec, exec, s[20:21]
	s_waitcnt vmcnt(7)
	v_mul_f32_e32 v41, v1, v205
	s_waitcnt vmcnt(6)
	v_mul_f32_e32 v43, v5, v209
	v_fmac_f32_e32 v41, v0, v204
	s_waitcnt vmcnt(5)
	v_mul_f32_e32 v47, v9, v213
	v_fmac_f32_e32 v43, v4, v208
	v_fmac_f32_e32 v41, v2, v206
	s_waitcnt vmcnt(4)
	v_mul_f32_e32 v51, v13, v217
	v_fmac_f32_e32 v47, v8, v212
	v_fmac_f32_e32 v43, v6, v210
	v_fmac_f32_e32 v41, v3, v207
	v_fmac_f32_e32 v51, v12, v216
	v_fmac_f32_e32 v47, v10, v214
	v_fmac_f32_e32 v43, v7, v211
	v_add_f32_e32 v41, 0, v41
	v_fmac_f32_e32 v51, v14, v218
	v_fmac_f32_e32 v47, v11, v215
	v_add_f32_e32 v41, v41, v43
	v_add_f32_e32 v41, v41, v47
	v_fmac_f32_e32 v51, v15, v219
	v_add_f32_e32 v41, v41, v51
	ds_bpermute_b32 v42, v34, v41
	s_waitcnt lgkmcnt(0)
	v_add_f32_e32 v41, v41, v42
	ds_bpermute_b32 v42, v35, v41
	s_waitcnt lgkmcnt(0)
	v_add_f32_e32 v41, v41, v42
	ds_bpermute_b32 v42, v36, v41
	s_waitcnt lgkmcnt(0)
	v_add_f32_e32 v41, v41, v42
	ds_bpermute_b32 v42, v37, v41
	s_and_saveexec_b64 s[20:21], s[0:1]
	s_cbranch_execz .LBB0_1630
	s_waitcnt lgkmcnt(0)
	v_add_f32_e32 v41, v41, v42
	v_mul_f32_e32 v41, 0x3d800000, v41
	ds_write_b32 v40, v41 offset:32
.LBB0_1630:
	s_or_b64 exec, exec, s[20:21]
	s_waitcnt vmcnt(3)
	v_mul_f32_e32 v41, v1, v225
	s_waitcnt vmcnt(2)
	v_mul_f32_e32 v43, v5, v229
	v_fmac_f32_e32 v41, v0, v224
	s_waitcnt vmcnt(1)
	v_mul_f32_e32 v47, v9, v233
	v_fmac_f32_e32 v43, v4, v228
	v_fmac_f32_e32 v41, v2, v226
	s_waitcnt vmcnt(0)
	v_mul_f32_e32 v51, v13, v237
	v_fmac_f32_e32 v47, v8, v232
	v_fmac_f32_e32 v43, v6, v230
	v_fmac_f32_e32 v41, v3, v227
	v_fmac_f32_e32 v51, v12, v236
	v_fmac_f32_e32 v47, v10, v234
	v_fmac_f32_e32 v43, v7, v231
	v_add_f32_e32 v41, 0, v41
	v_fmac_f32_e32 v51, v14, v238
	v_fmac_f32_e32 v47, v11, v235
	v_add_f32_e32 v41, v41, v43
	v_add_f32_e32 v41, v41, v47
	v_fmac_f32_e32 v51, v15, v239
	v_add_f32_e32 v41, v41, v51
	ds_bpermute_b32 v42, v34, v41
	s_waitcnt lgkmcnt(0)
	v_add_f32_e32 v41, v41, v42
	ds_bpermute_b32 v42, v35, v41
	s_waitcnt lgkmcnt(0)
	v_add_f32_e32 v41, v41, v42
	ds_bpermute_b32 v42, v36, v41
	s_waitcnt lgkmcnt(0)
	v_add_f32_e32 v41, v41, v42
	ds_bpermute_b32 v42, v37, v41
	s_and_saveexec_b64 s[20:21], s[0:1]
	s_cbranch_execz .LBB0_1632
	s_waitcnt lgkmcnt(0)
	v_add_f32_e32 v41, v41, v42
	v_mul_f32_e32 v41, 0x3d800000, v41
	ds_write_b32 v40, v41 offset:48
; DI void attn_sample_item(const Params& p, int l, int item, char* smem, bfr* Obuf) {
;     ...
; #pragma unroll 8
;   for (int ps = 0; ps < 16; ++ps) {
;     int mem = wid * 64 + ps * 4 + grp;
;     const float4* kr = (const float4*)(Kb + (size_t)mem * 1024);
;     float d = 0.f;
; #pragma unroll
;     for (int j = 0; j < 4; ++j) {
;       float4 k4 = kr[j * 16 + l16];
;       d += k4.x * q4[j].x + k4.y * q4[j].y + k4.z * q4[j].z + k4.w * q4[j].w;
;     }
;     d += __shfl_xor(d, 8);
;     d += __shfl_xor(d, 4);
;     d += __shfl_xor(d, 2);
;     d += __shfl_xor(d, 1);
;     if (l16 == 0) sc[mem] = d * 0.0625f;
;   }
.LBB0_1632:
	s_or_b64 exec, exec, s[20:21]
	v_lshl_add_u64 v[58:59], v[26:27], 0, s[18:19]
	s_waitcnt lgkmcnt(0)
	global_load_dwordx4 v[42:45], v[58:59], off offset:-512
	global_load_dwordx4 v[46:49], v[58:59], off offset:-256
	global_load_dwordx4 v[50:53], v[58:59], off
	global_load_dwordx4 v[54:57], v[58:59], off offset:256
	v_lshl_add_u64 v[240:241], v[28:29], 0, s[18:19]
	global_load_dwordx4 v[108:111], v[240:241], off offset:-512
	global_load_dwordx4 v[142:145], v[240:241], off offset:-256
	global_load_dwordx4 v[156:159], v[240:241], off
	global_load_dwordx4 v[200:203], v[240:241], off offset:256
	v_lshl_add_u64 v[240:241], v[32:33], 0, s[18:19]
	global_load_dwordx4 v[204:207], v[240:241], off offset:-512
	global_load_dwordx4 v[208:211], v[240:241], off offset:-256
	global_load_dwordx4 v[212:215], v[240:241], off
	global_load_dwordx4 v[216:219], v[240:241], off offset:256
	v_lshl_add_u64 v[240:241], v[30:31], 0, s[18:19]
	global_load_dwordx4 v[224:227], v[240:241], off offset:-512
	global_load_dwordx4 v[228:231], v[240:241], off offset:-256
	global_load_dwordx4 v[232:235], v[240:241], off
	global_load_dwordx4 v[236:239], v[240:241], off offset:256
	s_waitcnt vmcnt(15)
	v_mul_f32_e32 v41, v1, v43
	s_waitcnt vmcnt(14)
	v_mul_f32_e32 v43, v5, v47
	v_fmac_f32_e32 v41, v0, v42
	s_waitcnt vmcnt(13)
	v_mul_f32_e32 v47, v9, v51
	v_fmac_f32_e32 v43, v4, v46
	v_fmac_f32_e32 v41, v2, v44
	s_waitcnt vmcnt(12)
	v_mul_f32_e32 v51, v13, v55
	v_fmac_f32_e32 v47, v8, v50
	v_fmac_f32_e32 v43, v6, v48
	v_fmac_f32_e32 v41, v3, v45
	v_fmac_f32_e32 v51, v12, v54
	v_fmac_f32_e32 v47, v10, v52
	v_fmac_f32_e32 v43, v7, v49
	v_add_f32_e32 v41, 0, v41
	v_fmac_f32_e32 v51, v14, v56
	v_fmac_f32_e32 v47, v11, v53
	v_add_f32_e32 v41, v41, v43
	v_add_f32_e32 v41, v41, v47
	v_fmac_f32_e32 v51, v15, v57
	v_add_f32_e32 v41, v41, v51
	ds_bpermute_b32 v42, v34, v41
	s_waitcnt lgkmcnt(0)
	v_add_f32_e32 v41, v41, v42
	ds_bpermute_b32 v42, v35, v41
	s_waitcnt lgkmcnt(0)
	v_add_f32_e32 v41, v41, v42
	ds_bpermute_b32 v42, v36, v41
	s_waitcnt lgkmcnt(0)
	v_add_f32_e32 v41, v41, v42
	ds_bpermute_b32 v42, v37, v41
	s_and_saveexec_b64 s[20:21], s[0:1]
	s_cbranch_execz .LBB0_1634
	s_waitcnt lgkmcnt(0)
	v_add_f32_e32 v41, v41, v42
	v_mul_f32_e32 v41, 0x3d800000, v41
	ds_write_b32 v40, v41 offset:64
.LBB0_1634:
	s_or_b64 exec, exec, s[20:21]
	s_waitcnt vmcnt(11)
	v_mul_f32_e32 v41, v1, v109
	s_waitcnt vmcnt(10)
	v_mul_f32_e32 v43, v5, v143
	v_fmac_f32_e32 v41, v0, v108
	s_waitcnt vmcnt(9)
	v_mul_f32_e32 v47, v9, v157
	v_fmac_f32_e32 v43, v4, v142
	v_fmac_f32_e32 v41, v2, v110
	s_waitcnt vmcnt(8)
	v_mul_f32_e32 v51, v13, v201
	v_fmac_f32_e32 v47, v8, v156
	v_fmac_f32_e32 v43, v6, v144
	v_fmac_f32_e32 v41, v3, v111
	v_fmac_f32_e32 v51, v12, v200
	v_fmac_f32_e32 v47, v10, v158
	v_fmac_f32_e32 v43, v7, v145
	v_add_f32_e32 v41, 0, v41
	v_fmac_f32_e32 v51, v14, v202
	v_fmac_f32_e32 v47, v11, v159
	v_add_f32_e32 v41, v41, v43
	v_add_f32_e32 v41, v41, v47
	v_fmac_f32_e32 v51, v15, v203
	v_add_f32_e32 v41, v41, v51
	ds_bpermute_b32 v42, v34, v41
	s_waitcnt lgkmcnt(0)
	v_add_f32_e32 v41, v41, v42
	ds_bpermute_b32 v42, v35, v41
	s_waitcnt lgkmcnt(0)
	v_add_f32_e32 v41, v41, v42
	ds_bpermute_b32 v42, v36, v41
	s_waitcnt lgkmcnt(0)
	v_add_f32_e32 v41, v41, v42
	ds_bpermute_b32 v42, v37, v41
	s_and_saveexec_b64 s[20:21], s[0:1]
	s_cbranch_execz .LBB0_1636
	s_waitcnt lgkmcnt(0)
	v_add_f32_e32 v41, v41, v42
	v_mul_f32_e32 v41, 0x3d800000, v41
	ds_write_b32 v40, v41 offset:80
.LBB0_1636:
	s_or_b64 exec, exec, s[20:21]
	s_waitcnt vmcnt(7)
	v_mul_f32_e32 v41, v1, v205
	s_waitcnt vmcnt(6)
	v_mul_f32_e32 v43, v5, v209
	v_fmac_f32_e32 v41, v0, v204
	s_waitcnt vmcnt(5)
	v_mul_f32_e32 v47, v9, v213
	v_fmac_f32_e32 v43, v4, v208
	v_fmac_f32_e32 v41, v2, v206
	s_waitcnt vmcnt(4)
	v_mul_f32_e32 v51, v13, v217
	v_fmac_f32_e32 v47, v8, v212
	v_fmac_f32_e32 v43, v6, v210
	v_fmac_f32_e32 v41, v3, v207
	v_fmac_f32_e32 v51, v12, v216
	v_fmac_f32_e32 v47, v10, v214
	v_fmac_f32_e32 v43, v7, v211
	v_add_f32_e32 v41, 0, v41
	v_fmac_f32_e32 v51, v14, v218
	v_fmac_f32_e32 v47, v11, v215
	v_add_f32_e32 v41, v41, v43
	v_add_f32_e32 v41, v41, v47
	v_fmac_f32_e32 v51, v15, v219
	v_add_f32_e32 v41, v41, v51
	ds_bpermute_b32 v42, v34, v41
	s_waitcnt lgkmcnt(0)
	v_add_f32_e32 v41, v41, v42
	ds_bpermute_b32 v42, v35, v41
	s_waitcnt lgkmcnt(0)
	v_add_f32_e32 v41, v41, v42
	ds_bpermute_b32 v42, v36, v41
	s_waitcnt lgkmcnt(0)
	v_add_f32_e32 v41, v41, v42
	ds_bpermute_b32 v42, v37, v41
	s_and_saveexec_b64 s[20:21], s[0:1]
	s_cbranch_execz .LBB0_1638
	s_waitcnt lgkmcnt(0)
	v_add_f32_e32 v41, v41, v42
	v_mul_f32_e32 v41, 0x3d800000, v41
	ds_write_b32 v40, v41 offset:96
.LBB0_1638:
	s_or_b64 exec, exec, s[20:21]
	s_waitcnt vmcnt(3)
	v_mul_f32_e32 v41, v1, v225
	s_waitcnt vmcnt(2)
	v_mul_f32_e32 v43, v5, v229
	v_fmac_f32_e32 v41, v0, v224
	s_waitcnt vmcnt(1)
	v_mul_f32_e32 v47, v9, v233
	v_fmac_f32_e32 v43, v4, v228
	v_fmac_f32_e32 v41, v2, v226
	s_waitcnt vmcnt(0)
	v_mul_f32_e32 v51, v13, v237
	v_fmac_f32_e32 v47, v8, v232
	v_fmac_f32_e32 v43, v6, v230
	v_fmac_f32_e32 v41, v3, v227
	v_fmac_f32_e32 v51, v12, v236
	v_fmac_f32_e32 v47, v10, v234
	v_fmac_f32_e32 v43, v7, v231
	v_add_f32_e32 v41, 0, v41
	v_fmac_f32_e32 v51, v14, v238
	v_fmac_f32_e32 v47, v11, v235
	v_add_f32_e32 v41, v41, v43
	v_add_f32_e32 v41, v41, v47
	v_fmac_f32_e32 v51, v15, v239
	v_add_f32_e32 v41, v41, v51
	ds_bpermute_b32 v42, v34, v41
	s_waitcnt lgkmcnt(0)
	v_add_f32_e32 v41, v41, v42
	ds_bpermute_b32 v42, v35, v41
	s_waitcnt lgkmcnt(0)
	v_add_f32_e32 v41, v41, v42
	ds_bpermute_b32 v42, v36, v41
	s_waitcnt lgkmcnt(0)
	v_add_f32_e32 v41, v41, v42
	ds_bpermute_b32 v42, v37, v41
	s_and_saveexec_b64 s[20:21], s[0:1]
	s_cbranch_execz .LBB0_1623
	s_waitcnt lgkmcnt(0)
	v_add_f32_e32 v41, v41, v42
	v_mul_f32_e32 v41, 0x3d800000, v41
	ds_write_b32 v40, v41 offset:112
	s_branch .LBB0_1623
